# GEMM unit boundary: drop the two vmcnt(0) drains before the next unit's K loop (no VGPR-writing load is pending there; store data is read at issue)
# speedup vs baseline: 1.0036x; 1.0036x over previous
; #define PG8_STAGE(bufoff, gbase, voff) do { _Pragma("unroll") for (int _i = 0; _i < 2; ++_i) \
;         __builtin_amdgcn_global_load_lds((const unsigned*)((const char*)(gbase) + (voff)[_i]), (PG8_LAS unsigned*)(lds + (bufoff) + ldsw + _i * 8192), 16, 0, 0); } while (0)
; #define PG8_LDA(dst, b, h) do { _Pragma("unroll") for (int m = 0; m < 4; ++m) _Pragma("unroll") for (int k = 0; k < 2; ++k) dst[m][k] = *(const PG8_LAS bf16x8*)(lds + PG8_SA(b, h) + aoff + m * 2048 + k * 1024); } while (0)
; #define PG8_LDB(dst, b, h) do { _Pragma("unroll") for (int n = 0; n < 2; ++n) _Pragma("unroll") for (int k = 0; k < 2; ++k) dst[n][k] = *(const PG8_LAS bf16x8*)(lds + PG8_SB(b, h) + boff + n * 2048 + k * 1024); } while (0)
; #define PG8_WAIT_V(n) asm volatile("s_waitcnt vmcnt(" #n ")" ::: "memory")
; #define PG8_WAIT_L(n) asm volatile("s_waitcnt lgkmcnt(" #n ")" ::: "memory")
; #define PG8_BAR __builtin_amdgcn_s_barrier()
; template <class Epi, class Sched, bool ALIGN_EPI = false, bool SP2 = false>
; __device__ __forceinline__ void gemm_phase(PG8_LAS unsigned char* lds, const Gemm g, const Sched& S, const Epi& E) {
;     ...
;         for (int t = 0; t < nt; t += 2) {
;             const bool last = (t == nt - 2);
;             const char* a1 = cA + (size_t)(t + 1) * kstep;
;             const char* a2 = last ? nA : cA + (size_t)(t + 2) * kstep; const char* b2 = last ? nB : cB + (size_t)(t + 2) * kstep;
;             const char* a3 = a2 + kstep; const char* b3 = b2 + kstep;
;             if (last && has_next) S.a_ready(nxt);
;             if constexpr (SP2) {
;             PG8_LDB(B0, 0, 0); PG8_LDB(B1, 0, 1); PG8_SCHED; PG8_LDA(At, 0, 0); PG8_STAGE(PG8_SA(1, 1), a1 + hstep, voffA);
;             PG8_WAIT_V(8); PG8_WAIT_L(0); PG8_BAR; PG8_MMA(0, 0, At, B0); PG8_MMA(0, 1, At, B1); PG8_BAR; PG8_SCHED;
;             PG8_LDA(At, 0, 1); PG8_STAGE(PG8_SB(0, 0), b2, voffB); PG8_STAGE(PG8_SB(0, 1), b2 + hstep, voffB); PG8_STAGE(PG8_SA(0, 0), a2, voffA);
;             PG8_WAIT_V(8); PG8_WAIT_L(0); PG8_BAR; PG8_MMA(1, 0, At, B0); PG8_MMA(1, 1, At, B1); PG8_BAR; PG8_SCHED;
;     ...
; #pragma unroll
;         for (int a = 0; a < 2; ++a)
; #pragma unroll
;             for (int b = 0; b < 2; ++b)
; #pragma unroll
;                 for (int m = 0; m < 4; ++m)
; #pragma unroll
;                     for (int n = 0; n < 2; ++n) acc[a][b][m][n] = (f32x4){0.f, 0.f, 0.f, 0.f};
.LBB0_321:
	s_add_u32 s12, s16, 0x80
	s_addc_u32 s13, s17, 0
	s_add_u32 s16, s14, 0x100
	s_addc_u32 s17, s15, 0
	s_mov_b32 s14, 0
	s_nop 0
	s_nop 0
	s_waitcnt lgkmcnt(0)
	s_add_i32 s42, s14, 2
	s_add_u32 s43, s12, 0x80
	s_addc_u32 s15, s13, 0
	s_add_i32 s75, 0, 0x10000
	s_cmp_eq_u32 s25, s14
	s_cselect_b32 s15, s55, s15
	s_cselect_b32 s14, s54, s43
	s_cselect_b32 vcc_hi, s65, s17
	s_cselect_b32 vcc_lo, s64, s16
	s_add_i32 s43, 0, 0x14000
	v_add_u32_e32 v142, s75, v199
	v_add_u32_e32 v178, s43, v199
	ds_read_b128 v[130:133], v142
	ds_read_b128 v[134:137], v142 offset:1024
	ds_read_b128 v[138:141], v142 offset:2048
	ds_read_b128 v[142:145], v142 offset:3072
	ds_read_b128 v[170:173], v178
	ds_read_b128 v[174:177], v178 offset:1024
	ds_read_b128 v[202:205], v178 offset:2048
	ds_read_b128 v[206:209], v178 offset:3072
	v_lshl_add_u64 v[178:179], s[12:13], 0, v[166:167]
	s_add_i32 m0, s56, 0xc000
	ds_read_b128 v[210:213], v201
	ds_read_b128 v[214:217], v201 offset:1024
	ds_read_b128 v[218:221], v201 offset:2048
	ds_read_b128 v[222:225], v201 offset:3072
	ds_read_b128 v[226:229], v201 offset:4096
	ds_read_b128 v[230:233], v201 offset:5120
	ds_read_b128 v[234:237], v201 offset:6144
	ds_read_b128 v[238:241], v201 offset:7168
	global_load_lds_dwordx4 v[178:179], off
	v_lshl_add_u64 v[178:179], s[12:13], 0, v[168:169]
	s_add_i32 m0, s56, 0xe000
	s_nop 0
	global_load_lds_dwordx4 v[178:179], off
	s_waitcnt vmcnt(8)
	s_waitcnt lgkmcnt(0)
	s_barrier
	s_setprio 1
	s_waitcnt lgkmcnt(0)
	v_mfma_f32_16x16x32_bf16 v[126:129], v[130:133], v[210:213], 0
	v_mfma_f32_16x16x32_bf16 v[126:129], v[134:137], v[214:217], v[126:129]
	v_mfma_f32_16x16x32_bf16 v[122:125], v[138:141], v[210:213], 0
	v_mfma_f32_16x16x32_bf16 v[122:125], v[142:145], v[214:217], v[122:125]
	v_mfma_f32_16x16x32_bf16 v[110:113], v[130:133], v[218:221], 0
	v_mfma_f32_16x16x32_bf16 v[110:113], v[134:137], v[222:225], v[110:113]
	v_mfma_f32_16x16x32_bf16 v[106:109], v[138:141], v[218:221], 0
	v_mfma_f32_16x16x32_bf16 v[106:109], v[142:145], v[222:225], v[106:109]
	v_mfma_f32_16x16x32_bf16 v[94:97], v[130:133], v[226:229], 0
	v_mfma_f32_16x16x32_bf16 v[94:97], v[134:137], v[230:233], v[94:97]
	v_mfma_f32_16x16x32_bf16 v[90:93], v[138:141], v[226:229], 0
	v_mfma_f32_16x16x32_bf16 v[90:93], v[142:145], v[230:233], v[90:93]
	v_mfma_f32_16x16x32_bf16 v[78:81], v[130:133], v[234:237], 0
	v_mfma_f32_16x16x32_bf16 v[78:81], v[134:137], v[238:241], v[78:81]
	v_mfma_f32_16x16x32_bf16 v[74:77], v[138:141], v[234:237], 0
	v_mfma_f32_16x16x32_bf16 v[74:77], v[142:145], v[238:241], v[74:77]
	s_setprio 0
	s_setprio 1
	v_mfma_f32_16x16x32_bf16 v[118:121], v[170:173], v[210:213], 0
	v_mfma_f32_16x16x32_bf16 v[118:121], v[174:177], v[214:217], v[118:121]
	v_mfma_f32_16x16x32_bf16 v[114:117], v[202:205], v[210:213], 0
	v_mfma_f32_16x16x32_bf16 v[114:117], v[206:209], v[214:217], v[114:117]
	v_mfma_f32_16x16x32_bf16 v[102:105], v[170:173], v[218:221], 0
	v_mfma_f32_16x16x32_bf16 v[102:105], v[174:177], v[222:225], v[102:105]
	v_mfma_f32_16x16x32_bf16 v[98:101], v[202:205], v[218:221], 0
	v_mfma_f32_16x16x32_bf16 v[98:101], v[206:209], v[222:225], v[98:101]
	v_mfma_f32_16x16x32_bf16 v[86:89], v[170:173], v[226:229], 0
	v_mfma_f32_16x16x32_bf16 v[86:89], v[174:177], v[230:233], v[86:89]
	v_mfma_f32_16x16x32_bf16 v[82:85], v[202:205], v[226:229], 0
	v_mfma_f32_16x16x32_bf16 v[82:85], v[206:209], v[230:233], v[82:85]
	v_mfma_f32_16x16x32_bf16 v[70:73], v[170:173], v[234:237], 0
	v_mfma_f32_16x16x32_bf16 v[70:73], v[174:177], v[238:241], v[70:73]
	v_mfma_f32_16x16x32_bf16 v[66:69], v[202:205], v[234:237], 0
	v_mfma_f32_16x16x32_bf16 v[66:69], v[206:209], v[238:241], v[66:69]
	s_setprio 0
	s_barrier
	s_add_i32 s75, s75, s23
	v_lshl_add_u64 v[178:179], vcc, 0, v[0:1]
	s_mov_b32 m0, s75
	ds_read_b128 v[210:213], v201 offset:16384
	ds_read_b128 v[214:217], v201 offset:17408
	ds_read_b128 v[218:221], v201 offset:18432
	ds_read_b128 v[222:225], v201 offset:19456
	ds_read_b128 v[226:229], v201 offset:20480
	ds_read_b128 v[230:233], v201 offset:21504
	ds_read_b128 v[234:237], v201 offset:22528
	ds_read_b128 v[238:241], v201 offset:23552
	global_load_lds_dwordx4 v[178:179], off
	s_add_i32 m0, s75, 0x2000
	v_lshl_add_u64 v[242:243], vcc, 0, v[162:163]
	s_add_u32 vcc_lo, vcc_lo, s84
	s_addc_u32 vcc_hi, vcc_hi, 0
	s_add_i32 s43, s43, s23
	global_load_lds_dwordx4 v[242:243], off
	v_lshl_add_u64 v[244:245], vcc, 0, v[0:1]
	s_mov_b32 m0, s43
	v_lshl_add_u64 v[246:247], vcc, 0, v[162:163]
	global_load_lds_dwordx4 v[244:245], off
	s_add_i32 m0, s43, 0x2000
	v_lshl_add_u64 v[248:249], s[14:15], 0, v[158:159]
	global_load_lds_dwordx4 v[246:247], off
	s_mov_b32 m0, s56
	v_lshl_add_u64 v[250:251], s[14:15], 0, v[160:161]
	global_load_lds_dwordx4 v[248:249], off
	s_mov_b32 m0, s82
	s_nop 0
	global_load_lds_dwordx4 v[250:251], off
	s_waitcnt vmcnt(8)
	s_waitcnt lgkmcnt(0)
	s_barrier
; #define PG8_STAGE(bufoff, gbase, voff) do { _Pragma("unroll") for (int _i = 0; _i < 2; ++_i) \
;         __builtin_amdgcn_global_load_lds((const unsigned*)((const char*)(gbase) + (voff)[_i]), (PG8_LAS unsigned*)(lds + (bufoff) + ldsw + _i * 8192), 16, 0, 0); } while (0)
; #define PG8_LDA(dst, b, h) do { _Pragma("unroll") for (int m = 0; m < 4; ++m) _Pragma("unroll") for (int k = 0; k < 2; ++k) dst[m][k] = *(const PG8_LAS bf16x8*)(lds + PG8_SA(b, h) + aoff + m * 2048 + k * 1024); } while (0)
; #define PG8_LDB(dst, b, h) do { _Pragma("unroll") for (int n = 0; n < 2; ++n) _Pragma("unroll") for (int k = 0; k < 2; ++k) dst[n][k] = *(const PG8_LAS bf16x8*)(lds + PG8_SB(b, h) + boff + n * 2048 + k * 1024); } while (0)
; #define PG8_MMA(ai, bj, At, Bt) do { __builtin_amdgcn_s_setprio(1); _Pragma("unroll") for (int m = 0; m < 4; ++m) _Pragma("unroll") for (int n = 0; n < 2; ++n) _Pragma("unroll") for (int k = 0; k < 2; ++k) \
;         acc[ai][bj][m][n] = __builtin_amdgcn_mfma_f32_16x16x32_bf16(Bt[n][k], At[m][k], acc[ai][bj][m][n], 0, 0, 0); __builtin_amdgcn_s_setprio(0); } while (0)
; #define PG8_WAIT_V(n) asm volatile("s_waitcnt vmcnt(" #n ")" ::: "memory")
; #define PG8_WAIT_L(n) asm volatile("s_waitcnt lgkmcnt(" #n ")" ::: "memory")
; #define PG8_BAR __builtin_amdgcn_s_barrier()
; #define PG8_SCHED __builtin_amdgcn_sched_barrier(0)
; template <class Epi, class Sched, bool ALIGN_EPI = false, bool SP2 = false>
; __device__ __forceinline__ void gemm_phase(PG8_LAS unsigned char* lds, const Gemm g, const Sched& S, const Epi& E) {
;     ...
;             PG8_WAIT_V(8); PG8_WAIT_L(0); PG8_BAR; PG8_MMA(1, 0, At, B0); PG8_MMA(1, 1, At, B1); PG8_BAR; PG8_SCHED;
;             PG8_LDB(B0, 1, 0); PG8_LDB(B1, 1, 1); PG8_SCHED; PG8_LDA(At, 1, 0); PG8_STAGE(PG8_SA(0, 1), a2 + hstep, voffA);
;             PG8_WAIT_V(8); PG8_WAIT_L(0); PG8_BAR; PG8_MMA(0, 0, At, B0); PG8_MMA(0, 1, At, B1); PG8_BAR; PG8_SCHED;
	s_setprio 1
	s_waitcnt lgkmcnt(0)
	v_mfma_f32_16x16x32_bf16 v[62:65], v[130:133], v[210:213], 0
	v_mfma_f32_16x16x32_bf16 v[62:65], v[134:137], v[214:217], v[62:65]
	v_mfma_f32_16x16x32_bf16 v[58:61], v[138:141], v[210:213], 0
	v_mfma_f32_16x16x32_bf16 v[58:61], v[142:145], v[214:217], v[58:61]
	v_mfma_f32_16x16x32_bf16 v[46:49], v[130:133], v[218:221], 0
	v_mfma_f32_16x16x32_bf16 v[46:49], v[134:137], v[222:225], v[46:49]
	v_mfma_f32_16x16x32_bf16 v[42:45], v[138:141], v[218:221], 0
	v_mfma_f32_16x16x32_bf16 v[42:45], v[142:145], v[222:225], v[42:45]
	v_mfma_f32_16x16x32_bf16 v[30:33], v[130:133], v[226:229], 0
	v_mfma_f32_16x16x32_bf16 v[30:33], v[134:137], v[230:233], v[30:33]
	v_mfma_f32_16x16x32_bf16 v[26:29], v[138:141], v[226:229], 0
	v_mfma_f32_16x16x32_bf16 v[26:29], v[142:145], v[230:233], v[26:29]
	v_mfma_f32_16x16x32_bf16 v[14:17], v[130:133], v[234:237], 0
	v_mfma_f32_16x16x32_bf16 v[14:17], v[134:137], v[238:241], v[14:17]
	v_mfma_f32_16x16x32_bf16 v[10:13], v[138:141], v[234:237], 0
	v_mfma_f32_16x16x32_bf16 v[10:13], v[142:145], v[238:241], v[10:13]
	s_setprio 0
	s_setprio 1
	v_mfma_f32_16x16x32_bf16 v[54:57], v[170:173], v[210:213], 0
	v_mfma_f32_16x16x32_bf16 v[54:57], v[174:177], v[214:217], v[54:57]
	v_mfma_f32_16x16x32_bf16 v[50:53], v[202:205], v[210:213], 0
	v_mfma_f32_16x16x32_bf16 v[50:53], v[206:209], v[214:217], v[50:53]
	v_mfma_f32_16x16x32_bf16 v[38:41], v[170:173], v[218:221], 0
	v_mfma_f32_16x16x32_bf16 v[38:41], v[174:177], v[222:225], v[38:41]
	v_mfma_f32_16x16x32_bf16 v[34:37], v[202:205], v[218:221], 0
	v_mfma_f32_16x16x32_bf16 v[34:37], v[206:209], v[222:225], v[34:37]
	v_mfma_f32_16x16x32_bf16 v[22:25], v[170:173], v[226:229], 0
	v_mfma_f32_16x16x32_bf16 v[22:25], v[174:177], v[230:233], v[22:25]
	v_mfma_f32_16x16x32_bf16 v[18:21], v[202:205], v[226:229], 0
	v_mfma_f32_16x16x32_bf16 v[18:21], v[206:209], v[230:233], v[18:21]
	v_mfma_f32_16x16x32_bf16 v[6:9], v[170:173], v[234:237], 0
	v_mfma_f32_16x16x32_bf16 v[6:9], v[174:177], v[238:241], v[6:9]
	v_mfma_f32_16x16x32_bf16 v[2:5], v[202:205], v[234:237], 0
	v_mfma_f32_16x16x32_bf16 v[2:5], v[206:209], v[238:241], v[2:5]
	s_setprio 0
	s_barrier
	s_add_i32 s43, 0, 0x18000
	s_add_i32 s75, 0, 0x1c000
	v_add_u32_e32 v142, s43, v199
	v_add_u32_e32 v206, s75, v199
	ds_read_b128 v[130:133], v142
	ds_read_b128 v[134:137], v142 offset:1024
	ds_read_b128 v[138:141], v142 offset:2048
	ds_read_b128 v[142:145], v142 offset:3072
	ds_read_b128 v[170:173], v206
	ds_read_b128 v[174:177], v206 offset:1024
	ds_read_b128 v[202:205], v206 offset:2048
	ds_read_b128 v[206:209], v206 offset:3072
	s_add_u32 s14, s14, s84
	s_addc_u32 s15, s15, 0
	s_mov_b32 m0, s83
	v_lshl_add_u64 v[252:253], s[14:15], 0, v[158:159]
	ds_read_b128 v[210:213], v201 offset:32768
	ds_read_b128 v[214:217], v201 offset:33792
	ds_read_b128 v[218:221], v201 offset:34816
	ds_read_b128 v[222:225], v201 offset:35840
	ds_read_b128 v[226:229], v201 offset:36864
	ds_read_b128 v[230:233], v201 offset:37888
	ds_read_b128 v[234:237], v201 offset:38912
	ds_read_b128 v[238:241], v201 offset:39936
	global_load_lds_dwordx4 v[252:253], off
	v_lshl_add_u64 v[252:253], s[14:15], 0, v[160:161]
	s_mov_b32 m0, s24
	s_nop 0
	global_load_lds_dwordx4 v[252:253], off
	s_waitcnt vmcnt(8)
	s_waitcnt lgkmcnt(0)
	s_barrier
	s_setprio 1
	s_waitcnt lgkmcnt(0)
	v_mfma_f32_16x16x32_bf16 v[126:129], v[130:133], v[210:213], v[126:129]
	v_mfma_f32_16x16x32_bf16 v[126:129], v[134:137], v[214:217], v[126:129]
	v_mfma_f32_16x16x32_bf16 v[122:125], v[138:141], v[210:213], v[122:125]
	v_mfma_f32_16x16x32_bf16 v[122:125], v[142:145], v[214:217], v[122:125]
	v_mfma_f32_16x16x32_bf16 v[110:113], v[130:133], v[218:221], v[110:113]
	v_mfma_f32_16x16x32_bf16 v[110:113], v[134:137], v[222:225], v[110:113]
	v_mfma_f32_16x16x32_bf16 v[106:109], v[138:141], v[218:221], v[106:109]
	v_mfma_f32_16x16x32_bf16 v[106:109], v[142:145], v[222:225], v[106:109]
	v_mfma_f32_16x16x32_bf16 v[94:97], v[130:133], v[226:229], v[94:97]
	v_mfma_f32_16x16x32_bf16 v[94:97], v[134:137], v[230:233], v[94:97]
	v_mfma_f32_16x16x32_bf16 v[90:93], v[138:141], v[226:229], v[90:93]
	v_mfma_f32_16x16x32_bf16 v[90:93], v[142:145], v[230:233], v[90:93]
	v_mfma_f32_16x16x32_bf16 v[78:81], v[130:133], v[234:237], v[78:81]
	v_mfma_f32_16x16x32_bf16 v[78:81], v[134:137], v[238:241], v[78:81]
	v_mfma_f32_16x16x32_bf16 v[74:77], v[138:141], v[234:237], v[74:77]
	v_mfma_f32_16x16x32_bf16 v[74:77], v[142:145], v[238:241], v[74:77]
	s_setprio 0
	s_setprio 1
	v_mfma_f32_16x16x32_bf16 v[118:121], v[170:173], v[210:213], v[118:121]
	v_mfma_f32_16x16x32_bf16 v[118:121], v[174:177], v[214:217], v[118:121]
	v_mfma_f32_16x16x32_bf16 v[114:117], v[202:205], v[210:213], v[114:117]
	v_mfma_f32_16x16x32_bf16 v[114:117], v[206:209], v[214:217], v[114:117]
	v_mfma_f32_16x16x32_bf16 v[102:105], v[170:173], v[218:221], v[102:105]
	v_mfma_f32_16x16x32_bf16 v[102:105], v[174:177], v[222:225], v[102:105]
	v_mfma_f32_16x16x32_bf16 v[98:101], v[202:205], v[218:221], v[98:101]
	v_mfma_f32_16x16x32_bf16 v[98:101], v[206:209], v[222:225], v[98:101]
	v_mfma_f32_16x16x32_bf16 v[86:89], v[170:173], v[226:229], v[86:89]
	v_mfma_f32_16x16x32_bf16 v[86:89], v[174:177], v[230:233], v[86:89]
	v_mfma_f32_16x16x32_bf16 v[82:85], v[202:205], v[226:229], v[82:85]
	v_mfma_f32_16x16x32_bf16 v[82:85], v[206:209], v[230:233], v[82:85]
	v_mfma_f32_16x16x32_bf16 v[70:73], v[170:173], v[234:237], v[70:73]
	v_mfma_f32_16x16x32_bf16 v[70:73], v[174:177], v[238:241], v[70:73]
	v_mfma_f32_16x16x32_bf16 v[66:69], v[202:205], v[234:237], v[66:69]
	v_mfma_f32_16x16x32_bf16 v[66:69], v[206:209], v[238:241], v[66:69]
	s_setprio 0
	s_barrier
; #define PG8_STAGE(bufoff, gbase, voff) do { _Pragma("unroll") for (int _i = 0; _i < 2; ++_i) \
;         __builtin_amdgcn_global_load_lds((const unsigned*)((const char*)(gbase) + (voff)[_i]), (PG8_LAS unsigned*)(lds + (bufoff) + ldsw + _i * 8192), 16, 0, 0); } while (0)
; #define PG8_LDA(dst, b, h) do { _Pragma("unroll") for (int m = 0; m < 4; ++m) _Pragma("unroll") for (int k = 0; k < 2; ++k) dst[m][k] = *(const PG8_LAS bf16x8*)(lds + PG8_SA(b, h) + aoff + m * 2048 + k * 1024); } while (0)
; #define PG8_MMA(ai, bj, At, Bt) do { __builtin_amdgcn_s_setprio(1); _Pragma("unroll") for (int m = 0; m < 4; ++m) _Pragma("unroll") for (int n = 0; n < 2; ++n) _Pragma("unroll") for (int k = 0; k < 2; ++k) \
;         acc[ai][bj][m][n] = __builtin_amdgcn_mfma_f32_16x16x32_bf16(Bt[n][k], At[m][k], acc[ai][bj][m][n], 0, 0, 0); __builtin_amdgcn_s_setprio(0); } while (0)
; #define PG8_WAIT_V(n) asm volatile("s_waitcnt vmcnt(" #n ")" ::: "memory")
; #define PG8_WAIT_L(n) asm volatile("s_waitcnt lgkmcnt(" #n ")" ::: "memory")
; #define PG8_BAR __builtin_amdgcn_s_barrier()
; #define PG8_SCHED __builtin_amdgcn_sched_barrier(0)
; template <class Epi, class Sched, bool ALIGN_EPI = false, bool SP2 = false>
; __device__ __forceinline__ void gemm_phase(PG8_LAS unsigned char* lds, const Gemm g, const Sched& S, const Epi& E) {
;     ...
;             PG8_LDA(At, 1, 1); PG8_STAGE(PG8_SB(1, 0), b3, voffB); PG8_STAGE(PG8_SB(1, 1), b3 + hstep, voffB); PG8_STAGE(PG8_SA(1, 0), a3, voffA);
;             PG8_WAIT_V(8); PG8_WAIT_L(0); PG8_BAR; PG8_MMA(1, 0, At, B0); PG8_MMA(1, 1, At, B1); PG8_BAR; PG8_SCHED;
	s_add_i32 s14, s43, s23
	v_lshl_add_u64 v[178:179], v[178:179], 0, s[94:95]
	s_mov_b32 m0, s14
	ds_read_b128 v[210:213], v201 offset:49152
	ds_read_b128 v[214:217], v201 offset:50176
	ds_read_b128 v[218:221], v201 offset:51200
	ds_read_b128 v[222:225], v201 offset:52224
	ds_read_b128 v[226:229], v201 offset:53248
	ds_read_b128 v[230:233], v201 offset:54272
	ds_read_b128 v[234:237], v201 offset:55296
	ds_read_b128 v[238:241], v201 offset:56320
	global_load_lds_dwordx4 v[178:179], off
	v_lshl_add_u64 v[178:179], v[242:243], 0, s[94:95]
	s_add_i32 m0, s14, 0x2000
	s_add_i32 s14, s75, s23
	global_load_lds_dwordx4 v[178:179], off
	v_lshl_add_u64 v[178:179], v[244:245], 0, s[94:95]
	s_mov_b32 m0, s14
	s_nop 0
	global_load_lds_dwordx4 v[178:179], off
	v_lshl_add_u64 v[178:179], v[246:247], 0, s[94:95]
	s_add_i32 m0, s14, 0x2000
	s_nop 0
	global_load_lds_dwordx4 v[178:179], off
	v_lshl_add_u64 v[178:179], v[248:249], 0, s[94:95]
	s_mov_b32 m0, s63
	s_nop 0
	global_load_lds_dwordx4 v[178:179], off
	v_lshl_add_u64 v[178:179], v[250:251], 0, s[94:95]
	s_mov_b32 m0, s70
	s_nop 0
	global_load_lds_dwordx4 v[178:179], off
	s_waitcnt vmcnt(8)
	s_waitcnt lgkmcnt(0)
	s_barrier
	s_setprio 1
	s_waitcnt lgkmcnt(0)
	v_mfma_f32_16x16x32_bf16 v[62:65], v[130:133], v[210:213], v[62:65]
	v_mfma_f32_16x16x32_bf16 v[62:65], v[134:137], v[214:217], v[62:65]
	v_mfma_f32_16x16x32_bf16 v[58:61], v[138:141], v[210:213], v[58:61]
	v_mfma_f32_16x16x32_bf16 v[58:61], v[142:145], v[214:217], v[58:61]
	v_mfma_f32_16x16x32_bf16 v[46:49], v[130:133], v[218:221], v[46:49]
	v_mfma_f32_16x16x32_bf16 v[46:49], v[134:137], v[222:225], v[46:49]
	v_mfma_f32_16x16x32_bf16 v[42:45], v[138:141], v[218:221], v[42:45]
	v_mfma_f32_16x16x32_bf16 v[42:45], v[142:145], v[222:225], v[42:45]
	v_mfma_f32_16x16x32_bf16 v[30:33], v[130:133], v[226:229], v[30:33]
	v_mfma_f32_16x16x32_bf16 v[30:33], v[134:137], v[230:233], v[30:33]
	v_mfma_f32_16x16x32_bf16 v[26:29], v[138:141], v[226:229], v[26:29]
	v_mfma_f32_16x16x32_bf16 v[26:29], v[142:145], v[230:233], v[26:29]
	v_mfma_f32_16x16x32_bf16 v[14:17], v[130:133], v[234:237], v[14:17]
	v_mfma_f32_16x16x32_bf16 v[14:17], v[134:137], v[238:241], v[14:17]
	v_mfma_f32_16x16x32_bf16 v[10:13], v[138:141], v[234:237], v[10:13]
	v_mfma_f32_16x16x32_bf16 v[10:13], v[142:145], v[238:241], v[10:13]
	s_setprio 0
	s_setprio 1
	v_mfma_f32_16x16x32_bf16 v[54:57], v[170:173], v[210:213], v[54:57]
	v_mfma_f32_16x16x32_bf16 v[54:57], v[174:177], v[214:217], v[54:57]
	v_mfma_f32_16x16x32_bf16 v[50:53], v[202:205], v[210:213], v[50:53]
	v_mfma_f32_16x16x32_bf16 v[50:53], v[206:209], v[214:217], v[50:53]
	v_mfma_f32_16x16x32_bf16 v[38:41], v[170:173], v[218:221], v[38:41]
	v_mfma_f32_16x16x32_bf16 v[38:41], v[174:177], v[222:225], v[38:41]
	v_mfma_f32_16x16x32_bf16 v[34:37], v[202:205], v[218:221], v[34:37]
	v_mfma_f32_16x16x32_bf16 v[34:37], v[206:209], v[222:225], v[34:37]
	v_mfma_f32_16x16x32_bf16 v[22:25], v[170:173], v[226:229], v[22:25]
	v_mfma_f32_16x16x32_bf16 v[22:25], v[174:177], v[230:233], v[22:25]
	v_mfma_f32_16x16x32_bf16 v[18:21], v[202:205], v[226:229], v[18:21]
	v_mfma_f32_16x16x32_bf16 v[18:21], v[206:209], v[230:233], v[18:21]
	v_mfma_f32_16x16x32_bf16 v[6:9], v[170:173], v[234:237], v[6:9]
	v_mfma_f32_16x16x32_bf16 v[6:9], v[174:177], v[238:241], v[6:9]
	v_mfma_f32_16x16x32_bf16 v[2:5], v[202:205], v[234:237], v[2:5]
	v_mfma_f32_16x16x32_bf16 v[2:5], v[206:209], v[238:241], v[2:5]
	s_setprio 0
	s_barrier
	s_add_u32 s12, s12, 0x100
	s_addc_u32 s13, s13, 0
	s_add_u32 s16, s16, 0x100
	s_addc_u32 s17, s17, 0
	s_cmp_ge_u32 s42, s28
	s_mov_b32 s14, s42
	s_cbranch_scc0 .LBB0_322
	s_branch .Lk_done
